# hgrn unit queues: ticket counter bumped by 2 every other unit (half the same-line atomics)
# baseline (speedup 1.0000x reference)
; template <int WHICH>
; __device__ __forceinline__ HgRaw hg_load(KP& P_, int l, int u, int tid) {
;     const bf16_t* proj = (const bf16_t*)(p.ws + WS_PROJ);
;     const int idx = u - 780, bc = idx / 6, h = idx - bc * 6, t = tid >> 3, k0 = (tid & 7) * 8; const size_t row = (size_t)bc * 64 + t;
;     HgRaw r; r.q = (u32x4){0u, 0u, 0u, 0u};
;     if (WHICH) r.q = *(const u32x4*)(proj + row * NPROJ + h * 64 + k0);
;     r.f = *(const u32x4*)(proj + row * NPROJ + C_F + h * 64 + k0);
;     r.i = *(const u32x4*)(proj + row * NPROJ + C_I + h * 64 + k0);
;     const float* lbv = (const float*)(p.ws + TBL(T_LB, l)) + h * 64 + k0; r.lb0 = *(const f32x4*)lbv; r.lb1 = *(const f32x4*)(lbv + 4);
;     return r;
; template <int WHICH>
; __device__ void phase_mix_dyn(LAS unsigned char* lds, KP& P0, int l0) {
;     ...
;     HgRaw nxt; { KPtr P_ = P0; asm volatile("" : "+s"(P_.q)); nxt = hg_load<WHICH>(P_, l0, u, tid0); }
.LBB0_479:
	s_cmpk_gt_u32 s20, 0x923
	s_cbranch_scc1 .LBB0_502
	s_mov_b64 s[6:7], s[30:31]
	s_load_dwordx2 s[6:7], s[6:7], 0xe8
	s_add_i32 s12, s20, 0xfffffcf4
	s_mul_i32 s13, s12, 0xaaab
	s_lshr_b32 s13, s13, 18
	v_ashrrev_i32_e32 v2, 3, v138
	v_lshlrev_b32_e32 v0, 3, v138
	s_mul_i32 s14, s13, -6
	s_waitcnt vmcnt(0)
	v_and_b32_e32 v72, 56, v0
	v_lshl_add_u32 v0, s13, 6, v2
	s_waitcnt lgkmcnt(0)
	v_mov_b64_e32 v[8:9], s[6:7]
	s_add_i32 s14, s14, s12
	v_mad_i64_i32 v[8:9], s[12:13], v0, s9, v[8:9]
	s_lshl_b32 s12, s14, 6
	v_readlane_b32 s14, v255, 25
	v_readlane_b32 s15, v255, 26
	s_mov_b32 s22, s14
	s_ashr_i32 s13, s12, 31
	s_mul_i32 s15, s22, 0x44800
	s_mul_hi_i32 s14, s14, 0x44800
	s_add_u32 s15, s6, s15
	s_addc_u32 s14, s7, s14
	s_lshl_b64 s[6:7], s[12:13], 2
	v_lshl_add_u64 v[8:9], s[12:13], 1, v[8:9]
	v_lshlrev_b32_e32 v0, 1, v72
	s_add_u32 s6, s15, s6
	v_lshl_add_u64 v[8:9], v[8:9], 0, v[0:1]
	s_addc_u32 s7, s14, s7
	v_lshlrev_b32_e32 v0, 2, v72
	global_load_dwordx4 v[52:55], v[8:9], off
	global_load_dwordx4 v[68:71], v[8:9], off offset:768
	global_load_dwordx4 v[56:59], v[8:9], off offset:1536
	v_lshl_add_u64 v[8:9], s[6:7], 0, v[0:1]
	s_mov_b64 s[6:7], 0xef04800
	v_lshl_add_u64 v[10:11], v[8:9], 0, s[6:7]
	v_add_co_u32_e32 v8, vcc, 0xef04000, v8
	v_ashrrev_i32_e32 v3, 31, v2
	s_nop 0
	v_addc_co_u32_e32 v9, vcc, 0, v9, vcc
	global_load_dwordx4 v[64:67], v[8:9], off offset:2048
	global_load_dwordx4 v[60:63], v[10:11], off offset:16
	s_waitcnt vmcnt(0)
	s_mov_b32 s79, 0
	s_branch .LBB0_483

; template <int WHICH>
; __device__ void phase_mix_dyn(LAS unsigned char* lds, KP& P0, int l0) {
;     ...
;     for (;;) {
;         if (tid0 == 0) { n1 = n2; n2 = (int)__hip_atomic_fetch_add(ctr, 1u, __ATOMIC_RELAXED, __HIP_MEMORY_SCOPE_AGENT); }
;         KPtr P_ = P0; int l = l0; asm volatile("" : "+s"(P_.q), "+s"(l));
;         const HgRaw cur = nxt;
;         if (un < NMIXU) nxt = hg_load<WHICH>(P_, l, un, tid0);
.LBB0_483:
	v_readlane_b32 s6, v255, 25
	s_mov_b32 s12, s6
	s_mov_b64 s[46:47], s[30:31]
	s_load_dwordx2 s[42:43], s[46:47], 0xe8
	s_cmpk_lt_i32 s21, 0x924
	v_readlane_b32 s7, v255, 26
	s_cselect_b64 s[24:25], -1, 0
	s_cmpk_gt_i32 s21, 0x923
	s_cselect_b64 s[6:7], -1, 0
	v_mov_b64_e32 v[8:9], v[52:53]
	v_mov_b64_e32 v[12:13], v[68:69]
	v_mov_b64_e32 v[20:21], v[56:57]
	v_mov_b64_e32 v[16:17], v[64:65]
	s_and_saveexec_b64 s[14:15], s[40:41]
	s_cbranch_execz .Lhg_tk_c
	v_mov_b32_e32 v137, v136
	s_xor_b32 s79, s79, 1
	s_cmp_eq_u32 s79, 0
	s_cbranch_scc1 .Lhg_tk_c_2
	v_readlane_b32 s22, v255, 30
	v_readlane_b32 s23, v255, 31
	s_nop 4
	v_mov_b32_e32 v251, 2
	s_nop 0
	global_atomic_add v136, v1, v251, s[22:23] sc0
	s_branch .Lhg_tk_c
.Lhg_tk_c_2:
	v_add_u32_e32 v136, 1, v136

; template <int WHICH>
; __device__ __forceinline__ HgRaw hg_load(KP& P_, int l, int u, int tid) {
;     const bf16_t* proj = (const bf16_t*)(p.ws + WS_PROJ);
;     const int idx = u - 780, bc = idx / 6, h = idx - bc * 6, t = tid >> 3, k0 = (tid & 7) * 8; const size_t row = (size_t)bc * 64 + t;
;     HgRaw r; r.q = (u32x4){0u, 0u, 0u, 0u};
;     if (WHICH) r.q = *(const u32x4*)(proj + row * NPROJ + h * 64 + k0);
;     r.f = *(const u32x4*)(proj + row * NPROJ + C_F + h * 64 + k0);
;     r.i = *(const u32x4*)(proj + row * NPROJ + C_I + h * 64 + k0);
;     const float* lbv = (const float*)(p.ws + TBL(T_LB, l)) + h * 64 + k0; r.lb0 = *(const f32x4*)lbv; r.lb1 = *(const f32x4*)(lbv + 4);
;     return r;
; template <int WHICH>
; __device__ void phase_mix_dyn(LAS unsigned char* lds, KP& P0, int l0) {
;     ...
;     HgRaw nxt; { KPtr P_ = P0; asm volatile("" : "+s"(P_.q)); nxt = hg_load<WHICH>(P_, l0, u, tid0); }
.LBB0_687:
	s_cmpk_gt_u32 s13, 0x923
	s_cbranch_scc1 .LBB0_708
	s_mov_b64 s[14:15], s[30:31]
	s_load_dwordx2 s[14:15], s[14:15], 0xe8
	s_add_i32 s12, s13, 0xfffffcf4
	s_mul_i32 s20, s12, 0xaaab
	s_lshr_b32 s20, s20, 18
	v_ashrrev_i32_e32 v2, 3, v100
	v_lshlrev_b32_e32 v0, 3, v100
	s_mul_i32 s21, s20, -6
	s_waitcnt vmcnt(7)
	v_and_b32_e32 v40, 56, v0
	v_lshl_add_u32 v0, s20, 6, v2
	s_waitcnt lgkmcnt(0)
	v_mov_b64_e32 v[8:9], s[14:15]
	s_add_i32 s12, s21, s12
	v_mad_i64_i32 v[8:9], s[20:21], v0, s9, v[8:9]
	s_lshl_b32 s20, s12, 6
	v_readlane_b32 s22, v255, 25
	s_ashr_i32 s21, s20, 31
	s_mul_hi_i32 s12, s22, 0x44800
	s_mul_i32 s22, s22, 0x44800
	s_add_u32 s22, s14, s22
	s_addc_u32 s12, s15, s12
	s_lshl_b64 s[14:15], s[20:21], 2
	v_lshl_add_u64 v[8:9], s[20:21], 1, v[8:9]
	v_lshlrev_b32_e32 v0, 1, v40
	s_add_u32 s14, s22, s14
	v_lshl_add_u64 v[8:9], v[8:9], 0, v[0:1]
	s_addc_u32 s15, s12, s15
	v_lshlrev_b32_e32 v0, 2, v40
	global_load_dwordx4 v[36:39], v[8:9], off offset:768
	global_load_dwordx4 v[24:27], v[8:9], off offset:1536
	v_lshl_add_u64 v[8:9], s[14:15], 0, v[0:1]
	s_mov_b64 s[14:15], 0xef04800
	v_lshl_add_u64 v[10:11], v[8:9], 0, s[14:15]
	v_add_co_u32_e32 v8, vcc, 0xef04000, v8
	v_ashrrev_i32_e32 v3, 31, v2
	s_nop 0
	v_addc_co_u32_e32 v9, vcc, 0, v9, vcc
	global_load_dwordx4 v[32:35], v[8:9], off offset:2048
	global_load_dwordx4 v[28:31], v[10:11], off offset:16
	v_readlane_b32 s23, v255, 26
	s_waitcnt vmcnt(0)
	s_mov_b32 s79, 0
	s_branch .LBB0_691

; template <int WHICH>
; __device__ void phase_mix_dyn(LAS unsigned char* lds, KP& P0, int l0) {
;     ...
;     for (;;) {
;         if (tid0 == 0) { n1 = n2; n2 = (int)__hip_atomic_fetch_add(ctr, 1u, __ATOMIC_RELAXED, __HIP_MEMORY_SCOPE_AGENT); }
;         KPtr P_ = P0; int l = l0; asm volatile("" : "+s"(P_.q), "+s"(l));
;         const HgRaw cur = nxt;
;         if (un < NMIXU) nxt = hg_load<WHICH>(P_, l, un, tid0);
.LBB0_691:
	s_cmpk_lt_i32 s62, 0x924
	s_cselect_b64 s[22:23], -1, 0
	s_cmpk_gt_i32 s62, 0x923
	v_readlane_b32 s14, v255, 25
	s_cselect_b64 s[20:21], -1, 0
	v_mov_b64_e32 v[8:9], v[36:37]
	v_mov_b64_e32 v[12:13], v[24:25]
	v_mov_b64_e32 v[16:17], v[32:33]
	s_and_saveexec_b64 s[44:45], s[40:41]
	s_cbranch_execz .Lhg_tk_a
	v_mov_b32_e32 v99, v98
	s_xor_b32 s79, s79, 1
	s_cmp_eq_u32 s79, 0
	s_cbranch_scc1 .Lhg_tk_a_2
	s_nop 0
	v_mov_b32_e32 v251, 2
	s_nop 0
	global_atomic_add v98, v1, v251, s[6:7] sc0
	s_branch .Lhg_tk_a
.Lhg_tk_a_2:
	v_add_u32_e32 v98, 1, v98
